# hand-written phase_post (all row loads issued up front), context-hyena tap/conv loops with batched loads
# speedup vs baseline: 1.0773x; 1.0261x over previous
.LBB0_701:
	s_or_b64 exec, exec, s[2:3]
	v_add_u32_e32 v0, 0x100, v8
	v_ashrrev_i32_e32 v1, 31, v0
	v_ashrrev_i32_e32 v9, 31, v8
	v_mov_b32_e32 v14, 0
	v_lshl_add_u64 v[10:11], v[0:1], 2, s[36:37]
	v_lshl_add_u64 v[12:13], v[8:9], 2, s[36:37]
	s_mov_b32 s0, 0
	v_readlane_b32 s1, v254, 40
	v_mov_b32_e32 v15, v14
	s_waitcnt lgkmcnt(0)
	s_barrier
	v_mov_b32_e32 v17, s1
	v_lshlrev_b32_e32 v30, 2, v8
	s_mov_b32 s0, s36
	s_mov_b32 s1, s37
	global_load_dword v194, v30, s[0:1]
	s_add_u32 s0, s0, 0x400
	s_addc_u32 s1, s1, 0
	global_load_dword v195, v30, s[0:1]
	s_add_u32 s0, s0, 0x400
	s_addc_u32 s1, s1, 0
	global_load_dword v196, v30, s[0:1]
	s_add_u32 s0, s0, 0x400
	s_addc_u32 s1, s1, 0
	global_load_dword v197, v30, s[0:1]
	s_add_u32 s0, s0, 0x400
	s_addc_u32 s1, s1, 0
	global_load_dword v198, v30, s[0:1]
	s_add_u32 s0, s0, 0x400
	s_addc_u32 s1, s1, 0
	global_load_dword v199, v30, s[0:1]
	s_add_u32 s0, s0, 0x400
	s_addc_u32 s1, s1, 0
	global_load_dword v200, v30, s[0:1]
	s_add_u32 s0, s0, 0x400
	s_addc_u32 s1, s1, 0
	global_load_dword v201, v30, s[0:1]
	s_add_u32 s0, s0, 0x400
	s_addc_u32 s1, s1, 0
	global_load_dword v202, v30, s[0:1]
	s_add_u32 s0, s0, 0x400
	s_addc_u32 s1, s1, 0
	global_load_dword v203, v30, s[0:1]
	s_add_u32 s0, s0, 0x400
	s_addc_u32 s1, s1, 0
	global_load_dword v204, v30, s[0:1]
	s_add_u32 s0, s0, 0x400
	s_addc_u32 s1, s1, 0
	global_load_dword v205, v30, s[0:1]
	s_add_u32 s0, s0, 0x400
	s_addc_u32 s1, s1, 0
	global_load_dword v206, v30, s[0:1]
	s_add_u32 s0, s0, 0x400
	s_addc_u32 s1, s1, 0
	global_load_dword v207, v30, s[0:1]
	s_add_u32 s0, s0, 0x400
	s_addc_u32 s1, s1, 0
	global_load_dword v208, v30, s[0:1]
	s_add_u32 s0, s0, 0x400
	s_addc_u32 s1, s1, 0
	global_load_dword v209, v30, s[0:1]
	s_add_u32 s0, s0, 0x400
	s_addc_u32 s1, s1, 0
	global_load_dword v210, v30, s[0:1]
	s_add_u32 s0, s0, 0x400
	s_addc_u32 s1, s1, 0
	global_load_dword v211, v30, s[0:1]
	s_add_u32 s0, s0, 0x400
	s_addc_u32 s1, s1, 0
	global_load_dword v212, v30, s[0:1]
	s_add_u32 s0, s0, 0x400
	s_addc_u32 s1, s1, 0
	global_load_dword v213, v30, s[0:1]
	s_add_u32 s0, s0, 0x400
	s_addc_u32 s1, s1, 0
	global_load_dword v214, v30, s[0:1]
	s_add_u32 s0, s0, 0x400
	s_addc_u32 s1, s1, 0
	global_load_dword v215, v30, s[0:1]
	s_add_u32 s0, s0, 0x400
	s_addc_u32 s1, s1, 0
	global_load_dword v216, v30, s[0:1]
	s_add_u32 s0, s0, 0x400
	s_addc_u32 s1, s1, 0
	global_load_dword v217, v30, s[0:1]
	s_add_u32 s0, s0, 0x400
	s_addc_u32 s1, s1, 0
	global_load_dword v218, v30, s[0:1]
	s_add_u32 s0, s0, 0x400
	s_addc_u32 s1, s1, 0
	global_load_dword v219, v30, s[0:1]
	s_add_u32 s0, s0, 0x400
	s_addc_u32 s1, s1, 0
	global_load_dword v220, v30, s[0:1]
	s_add_u32 s0, s0, 0x400
	s_addc_u32 s1, s1, 0
	global_load_dword v221, v30, s[0:1]
	s_add_u32 s0, s0, 0x400
	s_addc_u32 s1, s1, 0
	global_load_dword v222, v30, s[0:1]
	s_add_u32 s0, s0, 0x400
	s_addc_u32 s1, s1, 0
	global_load_dword v223, v30, s[0:1]
	s_add_u32 s0, s0, 0x400
	s_addc_u32 s1, s1, 0
	global_load_dword v224, v30, s[0:1]
	s_add_u32 s0, s0, 0x400
	s_addc_u32 s1, s1, 0
	global_load_dword v225, v30, s[0:1]
	s_add_u32 s0, s0, 0x400
	s_addc_u32 s1, s1, 0
	global_load_dword v226, v30, s[0:1]
	s_add_u32 s0, s0, 0x400
	s_addc_u32 s1, s1, 0
	global_load_dword v227, v30, s[0:1]
	s_add_u32 s0, s0, 0x400
	s_addc_u32 s1, s1, 0
	global_load_dword v228, v30, s[0:1]
	s_add_u32 s0, s0, 0x400
	s_addc_u32 s1, s1, 0
	global_load_dword v229, v30, s[0:1]
	s_add_u32 s0, s0, 0x400
	s_addc_u32 s1, s1, 0
	global_load_dword v230, v30, s[0:1]
	s_add_u32 s0, s0, 0x400
	s_addc_u32 s1, s1, 0
	global_load_dword v231, v30, s[0:1]
	s_add_u32 s0, s0, 0x400
	s_addc_u32 s1, s1, 0
	global_load_dword v232, v30, s[0:1]
	s_add_u32 s0, s0, 0x400
	s_addc_u32 s1, s1, 0
	global_load_dword v233, v30, s[0:1]
	s_add_u32 s0, s0, 0x400
	s_addc_u32 s1, s1, 0
	global_load_dword v234, v30, s[0:1]
	s_add_u32 s0, s0, 0x400
	s_addc_u32 s1, s1, 0
	global_load_dword v235, v30, s[0:1]
	s_add_u32 s0, s0, 0x400
	s_addc_u32 s1, s1, 0
	global_load_dword v236, v30, s[0:1]
	s_add_u32 s0, s0, 0x400
	s_addc_u32 s1, s1, 0
	global_load_dword v237, v30, s[0:1]
	s_add_u32 s0, s0, 0x400
	s_addc_u32 s1, s1, 0
	global_load_dword v238, v30, s[0:1]
	s_add_u32 s0, s0, 0x400
	s_addc_u32 s1, s1, 0
	global_load_dword v239, v30, s[0:1]
	s_add_u32 s0, s0, 0x400
	s_addc_u32 s1, s1, 0
	global_load_dword v240, v30, s[0:1]
	s_add_u32 s0, s0, 0x400
	s_addc_u32 s1, s1, 0
	global_load_dword v241, v30, s[0:1]
	s_add_u32 s0, s0, 0x400
	s_addc_u32 s1, s1, 0
	global_load_dword v242, v30, s[0:1]
	s_add_u32 s0, s0, 0x400
	s_addc_u32 s1, s1, 0
	global_load_dword v243, v30, s[0:1]
	s_add_u32 s0, s0, 0x400
	s_addc_u32 s1, s1, 0
	global_load_dword v244, v30, s[0:1]
	s_add_u32 s0, s0, 0x400
	s_addc_u32 s1, s1, 0
	global_load_dword v245, v30, s[0:1]
	s_add_u32 s0, s0, 0x400
	s_addc_u32 s1, s1, 0
	global_load_dword v246, v30, s[0:1]
	s_add_u32 s0, s0, 0x400
	s_addc_u32 s1, s1, 0
	global_load_dword v247, v30, s[0:1]
	s_add_u32 s0, s0, 0x400
	s_addc_u32 s1, s1, 0
	global_load_dword v248, v30, s[0:1]
	s_add_u32 s0, s0, 0x400
	s_addc_u32 s1, s1, 0
	global_load_dword v249, v30, s[0:1]
	s_add_u32 s0, s0, 0x400
	s_addc_u32 s1, s1, 0
	global_load_dword v250, v30, s[0:1]
	s_add_u32 s0, s0, 0x400
	s_addc_u32 s1, s1, 0
	global_load_dword v251, v30, s[0:1]
	s_add_u32 s0, s0, 0x400
	s_addc_u32 s1, s1, 0
	global_load_dword v252, v30, s[0:1]
	s_add_u32 s0, s0, 0x400
	s_addc_u32 s1, s1, 0
	global_load_dword v253, v30, s[0:1]
	s_add_u32 s0, s0, 0x400
	s_addc_u32 s1, s1, 0
	ds_read_b128 v[18:21], v17
	ds_read_b128 v[22:25], v17 offset:256
	ds_read_b128 v[0:3], v17 offset:16
	ds_read_b128 v[4:7], v17 offset:272
	s_waitcnt vmcnt(28) lgkmcnt(2)
	v_fmac_f32_e32 v14, v194, v18
	v_fmac_f32_e32 v15, v194, v22
	v_fmac_f32_e32 v14, v195, v19
	v_fmac_f32_e32 v15, v195, v23
	v_fmac_f32_e32 v14, v196, v20
	v_fmac_f32_e32 v15, v196, v24
	v_fmac_f32_e32 v14, v197, v21
	v_fmac_f32_e32 v15, v197, v25
	ds_read_b128 v[18:21], v17 offset:32
	ds_read_b128 v[22:25], v17 offset:288
	s_waitcnt lgkmcnt(2)
	v_fmac_f32_e32 v14, v198, v0
	v_fmac_f32_e32 v15, v198, v4
	v_fmac_f32_e32 v14, v199, v1
	v_fmac_f32_e32 v15, v199, v5
	v_fmac_f32_e32 v14, v200, v2
	v_fmac_f32_e32 v15, v200, v6
	v_fmac_f32_e32 v14, v201, v3
	v_fmac_f32_e32 v15, v201, v7
	ds_read_b128 v[0:3], v17 offset:48
	ds_read_b128 v[4:7], v17 offset:304
	s_waitcnt lgkmcnt(2)
	v_fmac_f32_e32 v14, v202, v18
	v_fmac_f32_e32 v15, v202, v22
	v_fmac_f32_e32 v14, v203, v19
	v_fmac_f32_e32 v15, v203, v23
	v_fmac_f32_e32 v14, v204, v20
	v_fmac_f32_e32 v15, v204, v24
	v_fmac_f32_e32 v14, v205, v21
	v_fmac_f32_e32 v15, v205, v25
	ds_read_b128 v[18:21], v17 offset:64
	ds_read_b128 v[22:25], v17 offset:320
	s_waitcnt lgkmcnt(2)
	v_fmac_f32_e32 v14, v206, v0
	v_fmac_f32_e32 v15, v206, v4
	v_fmac_f32_e32 v14, v207, v1
	v_fmac_f32_e32 v15, v207, v5
	v_fmac_f32_e32 v14, v208, v2
	v_fmac_f32_e32 v15, v208, v6
	v_fmac_f32_e32 v14, v209, v3
	v_fmac_f32_e32 v15, v209, v7
	ds_read_b128 v[0:3], v17 offset:80
	ds_read_b128 v[4:7], v17 offset:336
	s_waitcnt lgkmcnt(2)
	v_fmac_f32_e32 v14, v210, v18
	v_fmac_f32_e32 v15, v210, v22
	v_fmac_f32_e32 v14, v211, v19
	v_fmac_f32_e32 v15, v211, v23
	v_fmac_f32_e32 v14, v212, v20
	v_fmac_f32_e32 v15, v212, v24
	v_fmac_f32_e32 v14, v213, v21
	v_fmac_f32_e32 v15, v213, v25
	ds_read_b128 v[18:21], v17 offset:96
	ds_read_b128 v[22:25], v17 offset:352
	s_waitcnt lgkmcnt(2)
	v_fmac_f32_e32 v14, v214, v0
	v_fmac_f32_e32 v15, v214, v4
	v_fmac_f32_e32 v14, v215, v1
	v_fmac_f32_e32 v15, v215, v5
	v_fmac_f32_e32 v14, v216, v2
	v_fmac_f32_e32 v15, v216, v6
	v_fmac_f32_e32 v14, v217, v3
	v_fmac_f32_e32 v15, v217, v7
	ds_read_b128 v[0:3], v17 offset:112
	ds_read_b128 v[4:7], v17 offset:368
	s_waitcnt lgkmcnt(2)
	v_fmac_f32_e32 v14, v218, v18
	v_fmac_f32_e32 v15, v218, v22
	v_fmac_f32_e32 v14, v219, v19
	v_fmac_f32_e32 v15, v219, v23
	v_fmac_f32_e32 v14, v220, v20
	v_fmac_f32_e32 v15, v220, v24
	v_fmac_f32_e32 v14, v221, v21
	v_fmac_f32_e32 v15, v221, v25
	ds_read_b128 v[18:21], v17 offset:128
	ds_read_b128 v[22:25], v17 offset:384
	s_waitcnt lgkmcnt(2)
	v_fmac_f32_e32 v14, v222, v0
	v_fmac_f32_e32 v15, v222, v4
	v_fmac_f32_e32 v14, v223, v1
	v_fmac_f32_e32 v15, v223, v5
	v_fmac_f32_e32 v14, v224, v2
	v_fmac_f32_e32 v15, v224, v6
	v_fmac_f32_e32 v14, v225, v3
	v_fmac_f32_e32 v15, v225, v7
	ds_read_b128 v[0:3], v17 offset:144
	ds_read_b128 v[4:7], v17 offset:400
	global_load_dword v26, v30, s[0:1]
	s_add_u32 s0, s0, 0x400
	s_addc_u32 s1, s1, 0
	global_load_dword v27, v30, s[0:1]
	s_add_u32 s0, s0, 0x400
	s_addc_u32 s1, s1, 0
	global_load_dword v28, v30, s[0:1]
	s_add_u32 s0, s0, 0x400
	s_addc_u32 s1, s1, 0
	global_load_dword v29, v30, s[0:1]
	s_add_u32 s0, s0, 0x400
	s_addc_u32 s1, s1, 0
	s_waitcnt vmcnt(0) lgkmcnt(2)
	v_fmac_f32_e32 v14, v226, v18
	v_fmac_f32_e32 v15, v226, v22
	v_fmac_f32_e32 v14, v227, v19
	v_fmac_f32_e32 v15, v227, v23
	v_fmac_f32_e32 v14, v228, v20
	v_fmac_f32_e32 v15, v228, v24
	v_fmac_f32_e32 v14, v229, v21
	v_fmac_f32_e32 v15, v229, v25
	ds_read_b128 v[18:21], v17 offset:160
	ds_read_b128 v[22:25], v17 offset:416
	s_waitcnt lgkmcnt(2)
	v_fmac_f32_e32 v14, v230, v0
	v_fmac_f32_e32 v15, v230, v4
	v_fmac_f32_e32 v14, v231, v1
	v_fmac_f32_e32 v15, v231, v5
	v_fmac_f32_e32 v14, v232, v2
	v_fmac_f32_e32 v15, v232, v6
	v_fmac_f32_e32 v14, v233, v3
	v_fmac_f32_e32 v15, v233, v7
	ds_read_b128 v[0:3], v17 offset:176
	ds_read_b128 v[4:7], v17 offset:432
	s_waitcnt lgkmcnt(2)
	v_fmac_f32_e32 v14, v234, v18
	v_fmac_f32_e32 v15, v234, v22
	v_fmac_f32_e32 v14, v235, v19
	v_fmac_f32_e32 v15, v235, v23
	v_fmac_f32_e32 v14, v236, v20
	v_fmac_f32_e32 v15, v236, v24
	v_fmac_f32_e32 v14, v237, v21
	v_fmac_f32_e32 v15, v237, v25
	ds_read_b128 v[18:21], v17 offset:192
	ds_read_b128 v[22:25], v17 offset:448
	s_waitcnt lgkmcnt(2)
	v_fmac_f32_e32 v14, v238, v0
	v_fmac_f32_e32 v15, v238, v4
	v_fmac_f32_e32 v14, v239, v1
	v_fmac_f32_e32 v15, v239, v5
	v_fmac_f32_e32 v14, v240, v2
	v_fmac_f32_e32 v15, v240, v6
	v_fmac_f32_e32 v14, v241, v3
	v_fmac_f32_e32 v15, v241, v7
	ds_read_b128 v[0:3], v17 offset:208
	ds_read_b128 v[4:7], v17 offset:464
	s_waitcnt lgkmcnt(2)
	v_fmac_f32_e32 v14, v242, v18
	v_fmac_f32_e32 v15, v242, v22
	v_fmac_f32_e32 v14, v243, v19
	v_fmac_f32_e32 v15, v243, v23
	v_fmac_f32_e32 v14, v244, v20
	v_fmac_f32_e32 v15, v244, v24
	v_fmac_f32_e32 v14, v245, v21
	v_fmac_f32_e32 v15, v245, v25
	ds_read_b128 v[18:21], v17 offset:224
	ds_read_b128 v[22:25], v17 offset:480
	s_waitcnt lgkmcnt(2)
	v_fmac_f32_e32 v14, v246, v0
	v_fmac_f32_e32 v15, v246, v4
	v_fmac_f32_e32 v14, v247, v1
	v_fmac_f32_e32 v15, v247, v5
	v_fmac_f32_e32 v14, v248, v2
	v_fmac_f32_e32 v15, v248, v6
	v_fmac_f32_e32 v14, v249, v3
	v_fmac_f32_e32 v15, v249, v7
	ds_read_b128 v[0:3], v17 offset:240
	ds_read_b128 v[4:7], v17 offset:496
	s_waitcnt lgkmcnt(2)
	v_fmac_f32_e32 v14, v250, v18
	v_fmac_f32_e32 v15, v250, v22
	v_fmac_f32_e32 v14, v251, v19
	v_fmac_f32_e32 v15, v251, v23
	v_fmac_f32_e32 v14, v252, v20
	v_fmac_f32_e32 v15, v252, v24
	v_fmac_f32_e32 v14, v253, v21
	v_fmac_f32_e32 v15, v253, v25
	s_waitcnt lgkmcnt(0)
	v_fmac_f32_e32 v14, v26, v0
	v_fmac_f32_e32 v15, v26, v4
	v_fmac_f32_e32 v14, v27, v1
	v_fmac_f32_e32 v15, v27, v5
	v_fmac_f32_e32 v14, v28, v2
	v_fmac_f32_e32 v15, v28, v6
	v_fmac_f32_e32 v14, v29, v3
	v_fmac_f32_e32 v15, v29, v7
	v_cvt_f32_i32_e32 v1, v8
	s_mov_b32 s2, 0xc37f0000
	v_cvt_f32_u32_e32 v0, s16
	s_lshl_b64 s[14:15], s[16:17], 9
	v_div_scale_f32 v2, s[0:1], s2, s2, v1
	v_rcp_f32_e32 v3, v2
	v_fmamk_f32 v0, v0, 0x3c44ade8, v186
	s_mov_b32 s0, 0x3fb8aa3b
	s_add_u32 s10, s26, s14
	v_fma_f32 v4, -v2, v3, 1.0
	v_fmac_f32_e32 v3, v4, v3
	v_div_scale_f32 v4, vcc, v1, s2, v1
	v_mul_f32_e32 v5, v4, v3
	v_fma_f32 v6, -v2, v5, v4
	v_fmac_f32_e32 v5, v6, v3
	v_fma_f32 v2, -v2, v5, v4
	v_div_fmas_f32 v2, v2, v3, v5
	v_div_fixup_f32 v1, v2, s2, v1
	v_mul_f32_e64 v0, |v0|, v1
	v_mul_f32_e32 v1, 0x3fb8aa3b, v0
	v_fma_f32 v2, v0, s0, -v1
	v_rndne_f32_e32 v3, v1
	v_fmac_f32_e32 v2, 0x32a5705f, v0
	v_sub_f32_e32 v1, v1, v3
	v_add_f32_e32 v1, v1, v2
	v_exp_f32_e32 v1, v1
	v_cvt_i32_f32_e32 v2, v3
	s_mov_b32 s0, 0xc2ce8ed0
	v_cmp_ngt_f32_e32 vcc, s0, v0
	s_mov_b32 s0, 0x42b17218
	v_ldexp_f32 v1, v1, v2
	v_cndmask_b32_e32 v1, 0, v1, vcc
	v_cmp_nlt_f32_e32 vcc, s0, v0
	s_addc_u32 s11, s27, s15
	s_lshl_b64 s[2:3], s[16:17], 2
	v_cndmask_b32_e32 v0, v190, v1, vcc
	s_add_u32 s0, s54, s2
	v_mul_f32_e32 v1, v0, v14
	v_mul_f32_e32 v0, v0, v15
	s_addc_u32 s1, s55, s3
	ds_write2st64_b32 v16, v1, v0 offset1:4
	s_add_u32 s12, s52, s2
	v_lshl_add_u64 v[0:1], v[8:9], 1, s[10:11]
	s_addc_u32 s13, s53, s3
	global_load_ushort v3, v[0:1], off
	global_load_dword v10, v165, s[0:1]
	global_load_dword v2, v184, s[12:13]
	v_cmp_lt_i32_e32 vcc, 0, v8
	v_mov_b32_e32 v164, v8
	s_waitcnt vmcnt(2)
	v_lshlrev_b32_e32 v3, 16, v3
	s_waitcnt vmcnt(0)
	v_fma_f32 v11, v2, v3, v10
	s_and_saveexec_b64 s[8:9], vcc
	s_cbranch_execz .LBB0_705
	v_lshl_add_u64 v[4:5], v[164:165], 1, s[10:11]
	global_load_ushort v4, v[4:5], off offset:-2
	s_waitcnt vmcnt(0)
	v_lshlrev_b32_e32 v4, 16, v4
	global_load_dword v3, v165, s[12:13]
	s_waitcnt vmcnt(0)
	v_fmac_f32_e32 v11, v3, v4

.Lhy_sl_loop:
	v_add_u32_e32 v37, s69, v18
	v_add_u32_e32 v19, s69, v16
	s_add_i32 s8, s0, s69
	v_mov_b32_e32 v40, s8
	v_cmp_gt_i32_e32 vcc, s1, v8
	v_add_u32_e32 v234, 1024, v37
	s_nop 0
	v_cndmask_b32_e32 v234, v19, v234, vcc
	ds_read_b32 v194, v234
	s_add_i32 s8, s1, 1
	v_cmp_gt_i32_e32 vcc, s8, v8
	v_add_u32_e32 v235, 1028, v37
	s_nop 0
	v_subrev_u32_e32 v36, 4, v19
	v_cndmask_b32_e32 v235, v36, v235, vcc
	ds_read_b32 v195, v235
	s_add_i32 s8, s1, 2
	v_cmp_gt_i32_e32 vcc, s8, v8
	v_add_u32_e32 v236, 1032, v37
	s_nop 0
	v_subrev_u32_e32 v36, 8, v19
	v_cndmask_b32_e32 v236, v36, v236, vcc
	ds_read_b32 v196, v236
	s_add_i32 s8, s1, 3
	v_cmp_gt_i32_e32 vcc, s8, v8
	v_add_u32_e32 v237, 1036, v37
	s_nop 0
	v_subrev_u32_e32 v36, 12, v19
	v_cndmask_b32_e32 v237, v36, v237, vcc
	ds_read_b32 v197, v237
	s_add_i32 s8, s1, 4
	v_cmp_gt_i32_e32 vcc, s8, v8
	v_add_u32_e32 v238, 1040, v37
	s_nop 0
	v_subrev_u32_e32 v36, 16, v19
	v_cndmask_b32_e32 v238, v36, v238, vcc
	ds_read_b32 v198, v238
	s_add_i32 s8, s1, 5
	v_cmp_gt_i32_e32 vcc, s8, v8
	v_add_u32_e32 v239, 1044, v37
	s_nop 0
	v_subrev_u32_e32 v36, 20, v19
	v_cndmask_b32_e32 v239, v36, v239, vcc
	ds_read_b32 v199, v239
	s_add_i32 s8, s1, 6
	v_cmp_gt_i32_e32 vcc, s8, v8
	v_add_u32_e32 v240, 1048, v37
	s_nop 0
	v_subrev_u32_e32 v36, 24, v19
	v_cndmask_b32_e32 v240, v36, v240, vcc
	ds_read_b32 v200, v240
	s_add_i32 s8, s1, 7
	v_cmp_gt_i32_e32 vcc, s8, v8
	v_add_u32_e32 v241, 1052, v37
	s_nop 0
	v_subrev_u32_e32 v36, 28, v19
	v_cndmask_b32_e32 v241, v36, v241, vcc
	ds_read_b32 v201, v241
	ds_read_b128 v[202:205], v40
	ds_read_b128 v[206:209], v40 offset:16
	ds_read_b128 v[210:213], v40 offset:1024
	ds_read_b128 v[214:217], v40 offset:1040
	ds_read_b128 v[218:221], v40 offset:2048
	ds_read_b128 v[222:225], v40 offset:2064
	ds_read_b128 v[226:229], v40 offset:3072
	ds_read_b128 v[230:233], v40 offset:3088
	s_waitcnt lgkmcnt(0)
	v_fmac_f32_e32 v6, v194, v202
	v_fmac_f32_e32 v7, v194, v210
	v_fmac_f32_e32 v4, v194, v218
	v_fmac_f32_e32 v5, v194, v226
	v_fmac_f32_e32 v6, v195, v203
	v_fmac_f32_e32 v7, v195, v211
	v_fmac_f32_e32 v4, v195, v219
	v_fmac_f32_e32 v5, v195, v227
	v_fmac_f32_e32 v6, v196, v204
	v_fmac_f32_e32 v7, v196, v212
	v_fmac_f32_e32 v4, v196, v220
	v_fmac_f32_e32 v5, v196, v228
	v_fmac_f32_e32 v6, v197, v205
	v_fmac_f32_e32 v7, v197, v213
	v_fmac_f32_e32 v4, v197, v221
	v_fmac_f32_e32 v5, v197, v229
	v_fmac_f32_e32 v6, v198, v206
	v_fmac_f32_e32 v7, v198, v214
	v_fmac_f32_e32 v4, v198, v222
	v_fmac_f32_e32 v5, v198, v230
	v_fmac_f32_e32 v6, v199, v207
	v_fmac_f32_e32 v7, v199, v215
	v_fmac_f32_e32 v4, v199, v223
	v_fmac_f32_e32 v5, v199, v231
	v_fmac_f32_e32 v6, v200, v208
	v_fmac_f32_e32 v7, v200, v216
	v_fmac_f32_e32 v4, v200, v224
	v_fmac_f32_e32 v5, v200, v232
	v_fmac_f32_e32 v6, v201, v209
	v_fmac_f32_e32 v7, v201, v217
	v_fmac_f32_e32 v4, v201, v225
	v_fmac_f32_e32 v5, v201, v233
	s_add_i32 s0, s0, 32
	s_add_i32 s1, s1, 8
	v_subrev_u32_e32 v16, 32, v16
	v_add_u32_e32 v18, 32, v18
	s_cmpk_lg_i32 s1, 0x100
	s_cbranch_scc1 .Lhy_sl_loop
	v_readlane_b32 s8, v254, 15
	v_readlane_b32 s10, v254, 17
	v_readlane_b32 s11, v254, 18
	s_add_u32 s0, s10, s2
	s_addc_u32 s1, s11, s3
	global_load_dword v2, v165, s[0:1]
	v_add_u32_e32 v0, 0x4000, v8
	s_lshl_b64 s[2:3], s[16:17], 1
	s_mov_b64 s[0:1], 0
	v_readlane_b32 s9, v254, 16
	s_waitcnt vmcnt(0)
	v_fma_f32 v1, v13, v2, v6
	v_mul_f32_e32 v1, v11, v1
	v_bfe_u32 v3, v1, 16, 1
	v_add3_u32 v3, v1, v3, s91
	v_ashrrev_i32_e32 v1, 31, v0
	v_lshlrev_b64 v[0:1], 12, v[0:1]
	v_lshl_add_u64 v[0:1], s[20:21], 0, v[0:1]
	v_lshl_add_u64 v[0:1], v[0:1], 0, s[2:3]
	v_fmac_f32_e32 v7, v15, v2
	global_store_short_d16_hi v[0:1], v3, off offset:2048
	v_mul_f32_e32 v1, v12, v7
	v_add_u32_e32 v0, 0x4100, v8
	v_bfe_u32 v3, v1, 16, 1
	v_add3_u32 v3, v1, v3, s91
	v_ashrrev_i32_e32 v1, 31, v0
	v_lshlrev_b64 v[0:1], 12, v[0:1]
	v_lshl_add_u64 v[0:1], s[20:21], 0, v[0:1]
	v_lshl_add_u64 v[0:1], v[0:1], 0, s[2:3]
	global_store_short_d16_hi v[0:1], v3, off offset:2048
	v_fma_f32 v1, v17, v2, v4
	v_mul_f32_e32 v1, v14, v1
	v_add_u32_e32 v0, 0x4200, v8
	v_bfe_u32 v3, v1, 16, 1
	v_add3_u32 v3, v1, v3, s91
	v_ashrrev_i32_e32 v1, 31, v0
	v_lshlrev_b64 v[0:1], 12, v[0:1]
	v_lshl_add_u64 v[0:1], s[20:21], 0, v[0:1]
	v_lshl_add_u64 v[0:1], v[0:1], 0, s[2:3]
	v_fmac_f32_e32 v5, v9, v2
	global_store_short_d16_hi v[0:1], v3, off offset:2048
	v_mul_f32_e32 v1, v10, v5
	v_add_u32_e32 v0, 0x4300, v8
	v_bfe_u32 v2, v1, 16, 1
	v_add3_u32 v2, v1, v2, s91
	v_ashrrev_i32_e32 v1, 31, v0
	v_lshlrev_b64 v[0:1], 12, v[0:1]
	v_lshl_add_u64 v[0:1], s[20:21], 0, v[0:1]
	v_lshl_add_u64 v[0:1], v[0:1], 0, s[2:3]
	global_store_short_d16_hi v[0:1], v2, off offset:2048
	s_barrier

.LBB0_1277:
.Lpost_entry:
	s_load_dwordx2 s[22:23], s[88:89], 0x0
	s_load_dwordx2 s[24:25], s[88:89], 0x10
	s_load_dwordx2 s[0:1], s[88:89], 0x30
	s_load_dwordx4 s[12:15], s[88:89], 0xc0
	s_load_dwordx2 s[26:27], s[88:89], 0xf0
	s_load_dwordx2 s[36:37], s[88:89], 0x110
	s_load_dwordx2 s[38:39], s[88:89], 0x130
	s_load_dwordx2 s[34:35], s[88:89], 0x160
	v_readlane_b32 s40, v255, 0
	v_readfirstlane_b32 s16, v167
	v_readlane_b32 s8, v254, 0
	v_readlane_b32 s9, v254, 1
	s_lshr_b32 s10, s16, 8
	s_mul_i32 s10, s10, s9
	s_add_u32 s10, s10, s8
	s_lshl_b32 s10, s10, 2
	s_bfe_u32 s16, s16, 0x20006
	s_add_u32 s16, s16, s10
	v_and_b32_e32 v228, 63, v167
	v_lshlrev_b32_e32 v226, 4, v228
	v_add_u32_e32 v227, 0x1000, v226
	v_lshlrev_b32_e32 v228, 3, v228
	s_waitcnt lgkmcnt(0)
	s_lshl_b32 s10, s40, 13
	s_add_u32 s12, s12, s10
	s_addc_u32 s13, s13, 0
	s_add_u32 s0, s0, 0x2000
	s_addc_u32 s1, s1, 0
	global_load_dwordx4 v[96:99], v226, s[12:13]
	global_load_dwordx4 v[100:103], v226, s[12:13] offset:1024
	global_load_dwordx4 v[104:107], v226, s[12:13] offset:2048
	global_load_dwordx4 v[108:111], v226, s[12:13] offset:3072
	global_load_dwordx4 v[112:115], v227, s[12:13]
	global_load_dwordx4 v[116:119], v227, s[12:13] offset:1024
	global_load_dwordx4 v[120:123], v227, s[12:13] offset:2048
	global_load_dwordx4 v[124:127], v227, s[12:13] offset:3072
	s_cmp_eq_u32 s40, 0
	s_cbranch_scc0 .Lpost_nopre
	global_load_dwordx4 v[194:197], v226, s[0:1]
	global_load_dwordx4 v[198:201], v226, s[0:1] offset:1024
	global_load_dwordx4 v[202:205], v226, s[0:1] offset:2048
	global_load_dwordx4 v[206:209], v226, s[0:1] offset:3072
	global_load_dwordx4 v[210:213], v227, s[0:1]
	global_load_dwordx4 v[214:217], v227, s[0:1] offset:1024
	global_load_dwordx4 v[218:221], v227, s[0:1] offset:2048
	global_load_dwordx4 v[222:225], v227, s[0:1] offset:3072
.Lpost_nopre:
	s_movk_i32 s9, 0x4000
	s_cmp_eq_u32 s40, 0
	s_cselect_b32 s9, 0x4400, s9
	s_cmp_lt_u32 s16, s9
	s_cbranch_scc0 .Lpost_done
.Lpost_row:
	s_lshl_b32 s10, s16, 13
	s_add_u32 s42, s38, s10
	s_addc_u32 s43, s39, 0
	s_lshr_b32 s8, s16, 12
	s_min_u32 s8, s8, 4
	s_add_u32 s11, s16, 0xffffc000
	s_lshl_b32 s11, s11, 13
	s_cmp_lt_u32 s16, 0x4000
	s_cbranch_scc0 .Lpost_ctxrow
	s_add_u32 s20, s14, s10
	s_addc_u32 s21, s15, 0
	s_add_u32 s0, s22, s10
	s_addc_u32 s1, s23, 0
	s_cmp_eq_u32 s40, 0
	s_cselect_b32 s0, s0, s20
	s_cselect_b32 s1, s1, s21
	s_branch .Lpost_ptrs
.Lpost_ctxrow:
	s_add_u32 s20, s34, s11
	s_addc_u32 s21, s35, 0
	s_add_u32 s0, s24, s11
	s_addc_u32 s1, s25, 0
.Lpost_ptrs:
	s_mul_i32 s9, s40, 5
	s_add_u32 s9, s9, s8
	s_mul_i32 s9, s9, 0x6000
	s_add_u32 s9, s9, 0x4000
	s_add_u32 s12, s26, s9
	s_addc_u32 s13, s27, 0
	global_load_dwordx4 v[0:3], v226, s[42:43]
	global_load_dwordx4 v[4:7], v226, s[42:43] offset:1024
	global_load_dwordx4 v[8:11], v226, s[42:43] offset:2048
	global_load_dwordx4 v[12:15], v226, s[42:43] offset:3072
	global_load_dwordx4 v[16:19], v227, s[42:43]
	global_load_dwordx4 v[20:23], v227, s[42:43] offset:1024
	global_load_dwordx4 v[24:27], v227, s[42:43] offset:2048
	global_load_dwordx4 v[28:31], v227, s[42:43] offset:3072
	global_load_dwordx4 v[32:35], v226, s[0:1]
	global_load_dwordx4 v[36:39], v226, s[0:1] offset:1024
	global_load_dwordx4 v[40:43], v226, s[0:1] offset:2048
	global_load_dwordx4 v[44:47], v226, s[0:1] offset:3072
	global_load_dwordx4 v[48:51], v227, s[0:1]
	global_load_dwordx4 v[52:55], v227, s[0:1] offset:1024
	global_load_dwordx4 v[56:59], v227, s[0:1] offset:2048
	global_load_dwordx4 v[60:63], v227, s[0:1] offset:3072
	global_load_dwordx4 v[64:67], v226, s[12:13]
	global_load_dwordx4 v[68:71], v226, s[12:13] offset:1024
	global_load_dwordx4 v[72:75], v226, s[12:13] offset:2048
	global_load_dwordx4 v[76:79], v226, s[12:13] offset:3072
	global_load_dwordx4 v[80:83], v227, s[12:13]
	global_load_dwordx4 v[84:87], v227, s[12:13] offset:1024
	global_load_dwordx4 v[88:91], v227, s[12:13] offset:2048
	global_load_dwordx4 v[92:95], v227, s[12:13] offset:3072
	s_waitcnt vmcnt(16)
	v_mul_f32_e32 v132, v0, v0
	v_mul_f32_e32 v133, v1, v1
	v_mul_f32_e32 v134, v2, v2
	v_mul_f32_e32 v135, v3, v3
	v_add_f32_e32 v128, v132, v133
	v_add_f32_e32 v128, v128, v134
	v_add_f32_e32 v128, v128, v135
	v_mul_f32_e32 v132, v4, v4
	v_mul_f32_e32 v133, v5, v5
	v_mul_f32_e32 v134, v6, v6
	v_mul_f32_e32 v135, v7, v7
	v_add_f32_e32 v129, v132, v133
	v_add_f32_e32 v129, v129, v134
	v_add_f32_e32 v129, v129, v135
	v_mul_f32_e32 v132, v8, v8
	v_mul_f32_e32 v133, v9, v9
	v_mul_f32_e32 v134, v10, v10
	v_mul_f32_e32 v135, v11, v11
	v_add_f32_e32 v130, v132, v133
	v_add_f32_e32 v130, v130, v134
	v_add_f32_e32 v130, v130, v135
	v_mul_f32_e32 v132, v12, v12
	v_mul_f32_e32 v133, v13, v13
	v_mul_f32_e32 v134, v14, v14
	v_mul_f32_e32 v135, v15, v15
	v_add_f32_e32 v131, v132, v133
	v_add_f32_e32 v131, v131, v134
	v_add_f32_e32 v131, v131, v135
	v_add_f32_e32 v229, v128, v129
	v_add_f32_e32 v229, v229, v130
	v_add_f32_e32 v229, v229, v131
	v_mul_f32_e32 v128, v17, v17
	v_fmac_f32_e32 v128, v16, v16
	v_fmac_f32_e32 v128, v18, v18
	v_fmac_f32_e32 v128, v19, v19
	v_mul_f32_e32 v129, v21, v21
	v_fmac_f32_e32 v129, v20, v20
	v_fmac_f32_e32 v129, v22, v22
	v_fmac_f32_e32 v129, v23, v23
	v_mul_f32_e32 v130, v25, v25
	v_fmac_f32_e32 v130, v24, v24
	v_fmac_f32_e32 v130, v26, v26
	v_fmac_f32_e32 v130, v27, v27
	v_mul_f32_e32 v131, v29, v29
	v_fmac_f32_e32 v131, v28, v28
	v_fmac_f32_e32 v131, v30, v30
	v_fmac_f32_e32 v131, v31, v31
	v_add_f32_e32 v229, v229, v128
	v_add_f32_e32 v229, v229, v129
	v_add_f32_e32 v229, v229, v130
	v_add_f32_e32 v229, v229, v131
	v_mov_b32_e32 v231, v229
	s_nop 1
	v_permlane32_swap_b32_e32 v229, v231
	s_nop 0
	v_add_f32_e32 v229, v229, v231
	v_mov_b32_e32 v231, v229
	s_nop 1
	v_permlane16_swap_b32_e32 v229, v231
	s_nop 0
	v_add_f32_e32 v229, v229, v231
	s_nop 1
	v_add_f32_dpp v229, v229, v229 row_ror:8 row_mask:0xf bank_mask:0xf
	s_nop 1
	v_add_f32_dpp v229, v229, v229 row_ror:4 row_mask:0xf bank_mask:0xf
	s_nop 1
	v_add_f32_dpp v229, v229, v229 row_ror:2 row_mask:0xf bank_mask:0xf
	s_nop 1
	v_add_f32_dpp v229, v229, v229 row_ror:1 row_mask:0xf bank_mask:0xf
	v_fmamk_f32 v229, v229, 0x3a000000, v166
	v_mul_f32_e32 v231, 0x4b800000, v229
	v_cmp_gt_f32_e32 vcc, s58, v229
	s_nop 1
	v_cndmask_b32_e32 v229, v229, v231, vcc
	v_rsq_f32_e32 v230, v229
	s_nop 0
	v_mul_f32_e32 v231, 0x45800000, v230
	v_cndmask_b32_e32 v230, v230, v231, vcc
	s_waitcnt vmcnt(0)
	v_mul_f32_e32 v0, v0, v64
	v_mul_f32_e32 v0, v0, v230
	v_fma_f32 v0, v0, v96, v32
	v_mul_f32_e32 v1, v1, v65
	v_mul_f32_e32 v1, v1, v230
	v_fma_f32 v1, v1, v97, v33
	v_mul_f32_e32 v2, v2, v66
	v_mul_f32_e32 v2, v2, v230
	v_fma_f32 v2, v2, v98, v34
	v_mul_f32_e32 v3, v3, v67
	v_mul_f32_e32 v3, v3, v230
	v_fma_f32 v3, v3, v99, v35
	v_mul_f32_e32 v4, v4, v68
	v_mul_f32_e32 v4, v4, v230
	v_fma_f32 v4, v4, v100, v36
	v_mul_f32_e32 v5, v5, v69
	v_mul_f32_e32 v5, v5, v230
	v_fma_f32 v5, v5, v101, v37
	v_mul_f32_e32 v6, v6, v70
	v_mul_f32_e32 v6, v6, v230
	v_fma_f32 v6, v6, v102, v38
	v_mul_f32_e32 v7, v7, v71
	v_mul_f32_e32 v7, v7, v230
	v_fma_f32 v7, v7, v103, v39
	v_mul_f32_e32 v8, v8, v72
	v_mul_f32_e32 v8, v8, v230
	v_fma_f32 v8, v8, v104, v40
	v_mul_f32_e32 v9, v9, v73
	v_mul_f32_e32 v9, v9, v230
	v_fma_f32 v9, v9, v105, v41
	v_mul_f32_e32 v10, v10, v74
	v_mul_f32_e32 v10, v10, v230
	v_fma_f32 v10, v10, v106, v42
	v_mul_f32_e32 v11, v11, v75
	v_mul_f32_e32 v11, v11, v230
	v_fma_f32 v11, v11, v107, v43
	v_mul_f32_e32 v12, v12, v76
	v_mul_f32_e32 v12, v12, v230
	v_fma_f32 v12, v12, v108, v44
	v_mul_f32_e32 v13, v13, v77
	v_mul_f32_e32 v13, v13, v230
	v_fma_f32 v13, v13, v109, v45
	v_mul_f32_e32 v14, v14, v78
	v_mul_f32_e32 v14, v14, v230
	v_fma_f32 v14, v14, v110, v46
	v_mul_f32_e32 v15, v15, v79
	v_mul_f32_e32 v15, v15, v230
	v_fma_f32 v15, v15, v111, v47
	v_mul_f32_e32 v16, v16, v80
	v_mul_f32_e32 v16, v16, v230
	v_fma_f32 v16, v16, v112, v48
	v_mul_f32_e32 v17, v17, v81
	v_mul_f32_e32 v17, v17, v230
	v_fma_f32 v17, v17, v113, v49
	v_mul_f32_e32 v18, v18, v82
	v_mul_f32_e32 v18, v18, v230
	v_fma_f32 v18, v18, v114, v50
	v_mul_f32_e32 v19, v19, v83
	v_mul_f32_e32 v19, v19, v230
	v_fma_f32 v19, v19, v115, v51
	v_mul_f32_e32 v20, v20, v84
	v_mul_f32_e32 v20, v20, v230
	v_fma_f32 v20, v20, v116, v52
	v_mul_f32_e32 v21, v21, v85
	v_mul_f32_e32 v21, v21, v230
	v_fma_f32 v21, v21, v117, v53
	v_mul_f32_e32 v22, v22, v86
	v_mul_f32_e32 v22, v22, v230
	v_fma_f32 v22, v22, v118, v54
	v_mul_f32_e32 v23, v23, v87
	v_mul_f32_e32 v23, v23, v230
	v_fma_f32 v23, v23, v119, v55
	v_mul_f32_e32 v24, v24, v88
	v_mul_f32_e32 v24, v24, v230
	v_fma_f32 v24, v24, v120, v56
	v_mul_f32_e32 v25, v25, v89
	v_mul_f32_e32 v25, v25, v230
	v_fma_f32 v25, v25, v121, v57
	v_mul_f32_e32 v26, v26, v90
	v_mul_f32_e32 v26, v26, v230
	v_fma_f32 v26, v26, v122, v58
	v_mul_f32_e32 v27, v27, v91
	v_mul_f32_e32 v27, v27, v230
	v_fma_f32 v27, v27, v123, v59
	v_mul_f32_e32 v28, v28, v92
	v_mul_f32_e32 v28, v28, v230
	v_fma_f32 v28, v28, v124, v60
	v_mul_f32_e32 v29, v29, v93
	v_mul_f32_e32 v29, v29, v230
	v_fma_f32 v29, v29, v125, v61
	v_mul_f32_e32 v30, v30, v94
	v_mul_f32_e32 v30, v30, v230
	v_fma_f32 v30, v30, v126, v62
	v_mul_f32_e32 v31, v31, v95
	v_mul_f32_e32 v31, v31, v230
	v_fma_f32 v31, v31, v127, v63
	global_store_dwordx4 v226, v[0:3], s[20:21]
	global_store_dwordx4 v226, v[4:7], s[20:21] offset:1024
	global_store_dwordx4 v226, v[8:11], s[20:21] offset:2048
	global_store_dwordx4 v226, v[12:15], s[20:21] offset:3072
	global_store_dwordx4 v227, v[16:19], s[20:21]
	global_store_dwordx4 v227, v[20:23], s[20:21] offset:1024
	global_store_dwordx4 v227, v[24:27], s[20:21] offset:2048
	global_store_dwordx4 v227, v[28:31], s[20:21] offset:3072
	s_cmp_eq_u32 s40, 0
	s_cbranch_scc0 .Lpost_next
	s_add_u32 s9, s8, 5
	s_mul_i32 s9, s9, 0x6000
	s_add_u32 s12, s26, s9
	s_addc_u32 s13, s27, 0
	s_add_u32 s0, s12, 0x2000
	s_addc_u32 s1, s13, 0
	global_load_dwordx4 v[32:35], v226, s[12:13]
	global_load_dwordx4 v[36:39], v226, s[12:13] offset:1024
	global_load_dwordx4 v[40:43], v226, s[12:13] offset:2048
	global_load_dwordx4 v[44:47], v226, s[12:13] offset:3072
	global_load_dwordx4 v[48:51], v227, s[12:13]
	global_load_dwordx4 v[52:55], v227, s[12:13] offset:1024
	global_load_dwordx4 v[56:59], v227, s[12:13] offset:2048
	global_load_dwordx4 v[60:63], v227, s[12:13] offset:3072
	global_load_dwordx4 v[64:67], v226, s[0:1]
	global_load_dwordx4 v[68:71], v226, s[0:1] offset:1024
	global_load_dwordx4 v[72:75], v226, s[0:1] offset:2048
	global_load_dwordx4 v[76:79], v226, s[0:1] offset:3072
	global_load_dwordx4 v[80:83], v227, s[0:1]
	global_load_dwordx4 v[84:87], v227, s[0:1] offset:1024
	global_load_dwordx4 v[88:91], v227, s[0:1] offset:2048
	global_load_dwordx4 v[92:95], v227, s[0:1] offset:3072
	s_lshl_b32 s10, s16, 12
	s_add_u32 s10, s36, s10
	s_addc_u32 s11, s37, 0
	v_mul_f32_e32 v132, v0, v0
	v_mul_f32_e32 v133, v1, v1
	v_mul_f32_e32 v134, v2, v2
	v_mul_f32_e32 v135, v3, v3
	v_add_f32_e32 v128, v132, v133
	v_add_f32_e32 v128, v128, v134
	v_add_f32_e32 v128, v128, v135
	v_mul_f32_e32 v132, v4, v4
	v_mul_f32_e32 v133, v5, v5
	v_mul_f32_e32 v134, v6, v6
	v_mul_f32_e32 v135, v7, v7
	v_add_f32_e32 v129, v132, v133
	v_add_f32_e32 v129, v129, v134
	v_add_f32_e32 v129, v129, v135
	v_mul_f32_e32 v132, v8, v8
	v_mul_f32_e32 v133, v9, v9
	v_mul_f32_e32 v134, v10, v10
	v_mul_f32_e32 v135, v11, v11
	v_add_f32_e32 v130, v132, v133
	v_add_f32_e32 v130, v130, v134
	v_add_f32_e32 v130, v130, v135
	v_mul_f32_e32 v132, v12, v12
	v_mul_f32_e32 v133, v13, v13
	v_mul_f32_e32 v134, v14, v14
	v_mul_f32_e32 v135, v15, v15
	v_add_f32_e32 v131, v132, v133
	v_add_f32_e32 v131, v131, v134
	v_add_f32_e32 v131, v131, v135
	v_add_f32_e32 v229, v128, v129
	v_add_f32_e32 v229, v229, v130
	v_add_f32_e32 v229, v229, v131
	v_mul_f32_e32 v128, v17, v17
	v_fmac_f32_e32 v128, v16, v16
	v_fmac_f32_e32 v128, v18, v18
	v_fmac_f32_e32 v128, v19, v19
	v_mul_f32_e32 v129, v21, v21
	v_fmac_f32_e32 v129, v20, v20
	v_fmac_f32_e32 v129, v22, v22
	v_fmac_f32_e32 v129, v23, v23
	v_mul_f32_e32 v130, v25, v25
	v_fmac_f32_e32 v130, v24, v24
	v_fmac_f32_e32 v130, v26, v26
	v_fmac_f32_e32 v130, v27, v27
	v_mul_f32_e32 v131, v29, v29
	v_fmac_f32_e32 v131, v28, v28
	v_fmac_f32_e32 v131, v30, v30
	v_fmac_f32_e32 v131, v31, v31
	v_add_f32_e32 v229, v229, v128
	v_add_f32_e32 v229, v229, v129
	v_add_f32_e32 v229, v229, v130
	v_add_f32_e32 v229, v229, v131
	v_mov_b32_e32 v231, v229
	s_nop 1
	v_permlane32_swap_b32_e32 v229, v231
	s_nop 0
	v_add_f32_e32 v229, v229, v231
	v_mov_b32_e32 v231, v229
	s_nop 1
	v_permlane16_swap_b32_e32 v229, v231
	s_nop 0
	v_add_f32_e32 v229, v229, v231
	s_nop 1
	v_add_f32_dpp v229, v229, v229 row_ror:8 row_mask:0xf bank_mask:0xf
	s_nop 1
	v_add_f32_dpp v229, v229, v229 row_ror:4 row_mask:0xf bank_mask:0xf
	s_nop 1
	v_add_f32_dpp v229, v229, v229 row_ror:2 row_mask:0xf bank_mask:0xf
	s_nop 1
	v_add_f32_dpp v229, v229, v229 row_ror:1 row_mask:0xf bank_mask:0xf
	v_fmamk_f32 v229, v229, 0x3a000000, v166
	v_mul_f32_e32 v231, 0x4b800000, v229
	v_cmp_gt_f32_e32 vcc, s58, v229
	s_nop 1
	v_cndmask_b32_e32 v229, v229, v231, vcc
	v_rsq_f32_e32 v230, v229
	s_nop 0
	v_mul_f32_e32 v231, 0x45800000, v230
	v_cndmask_b32_e32 v230, v230, v231, vcc
	s_waitcnt vmcnt(0)
	v_mul_f32_e32 v0, v0, v230
	v_mul_f32_e32 v0, v194, v0
	v_add_f32_e32 v64, 1.0, v64
	v_fma_f32 v0, v64, v0, v32
	v_mul_f32_e32 v1, v1, v230
	v_mul_f32_e32 v1, v195, v1
	v_add_f32_e32 v65, 1.0, v65
	v_fma_f32 v1, v65, v1, v33
	v_mul_f32_e32 v2, v2, v230
	v_mul_f32_e32 v2, v196, v2
	v_add_f32_e32 v66, 1.0, v66
	v_fma_f32 v2, v66, v2, v34
	v_mul_f32_e32 v3, v3, v230
	v_mul_f32_e32 v3, v197, v3
	v_add_f32_e32 v67, 1.0, v67
	v_fma_f32 v3, v67, v3, v35
	v_cvt_pk_bf16_f32 v0, v0, v1
	v_cvt_pk_bf16_f32 v1, v2, v3
	global_store_dwordx2 v228, v[0:1], s[10:11]
	v_mul_f32_e32 v4, v4, v230
	v_mul_f32_e32 v4, v198, v4
	v_add_f32_e32 v68, 1.0, v68
	v_fma_f32 v4, v68, v4, v36
	v_mul_f32_e32 v5, v5, v230
	v_mul_f32_e32 v5, v199, v5
	v_add_f32_e32 v69, 1.0, v69
	v_fma_f32 v5, v69, v5, v37
	v_mul_f32_e32 v6, v6, v230
	v_mul_f32_e32 v6, v200, v6
	v_add_f32_e32 v70, 1.0, v70
	v_fma_f32 v6, v70, v6, v38
	v_mul_f32_e32 v7, v7, v230
	v_mul_f32_e32 v7, v201, v7
	v_add_f32_e32 v71, 1.0, v71
	v_fma_f32 v7, v71, v7, v39
	v_cvt_pk_bf16_f32 v4, v4, v5
	v_cvt_pk_bf16_f32 v5, v6, v7
	global_store_dwordx2 v228, v[4:5], s[10:11] offset:512
	v_mul_f32_e32 v8, v8, v230
	v_mul_f32_e32 v8, v202, v8
	v_add_f32_e32 v72, 1.0, v72
	v_fma_f32 v8, v72, v8, v40
	v_mul_f32_e32 v9, v9, v230
	v_mul_f32_e32 v9, v203, v9
	v_add_f32_e32 v73, 1.0, v73
	v_fma_f32 v9, v73, v9, v41
	v_mul_f32_e32 v10, v10, v230
	v_mul_f32_e32 v10, v204, v10
	v_add_f32_e32 v74, 1.0, v74
	v_fma_f32 v10, v74, v10, v42
	v_mul_f32_e32 v11, v11, v230
	v_mul_f32_e32 v11, v205, v11
	v_add_f32_e32 v75, 1.0, v75
	v_fma_f32 v11, v75, v11, v43
	v_cvt_pk_bf16_f32 v8, v8, v9
	v_cvt_pk_bf16_f32 v9, v10, v11
	global_store_dwordx2 v228, v[8:9], s[10:11] offset:1024
	v_mul_f32_e32 v12, v12, v230
	v_mul_f32_e32 v12, v206, v12
	v_add_f32_e32 v76, 1.0, v76
	v_fma_f32 v12, v76, v12, v44
	v_mul_f32_e32 v13, v13, v230
	v_mul_f32_e32 v13, v207, v13
	v_add_f32_e32 v77, 1.0, v77
	v_fma_f32 v13, v77, v13, v45
	v_mul_f32_e32 v14, v14, v230
	v_mul_f32_e32 v14, v208, v14
	v_add_f32_e32 v78, 1.0, v78
	v_fma_f32 v14, v78, v14, v46
	v_mul_f32_e32 v15, v15, v230
	v_mul_f32_e32 v15, v209, v15
	v_add_f32_e32 v79, 1.0, v79
	v_fma_f32 v15, v79, v15, v47
	v_cvt_pk_bf16_f32 v12, v12, v13
	v_cvt_pk_bf16_f32 v13, v14, v15
	global_store_dwordx2 v228, v[12:13], s[10:11] offset:1536
	v_mul_f32_e32 v16, v16, v230
	v_mul_f32_e32 v16, v210, v16
	v_add_f32_e32 v80, 1.0, v80
	v_fma_f32 v16, v80, v16, v48
	v_mul_f32_e32 v17, v17, v230
	v_mul_f32_e32 v17, v211, v17
	v_add_f32_e32 v81, 1.0, v81
	v_fma_f32 v17, v81, v17, v49
	v_mul_f32_e32 v18, v18, v230
	v_mul_f32_e32 v18, v212, v18
	v_add_f32_e32 v82, 1.0, v82
	v_fma_f32 v18, v82, v18, v50
	v_mul_f32_e32 v19, v19, v230
	v_mul_f32_e32 v19, v213, v19
	v_add_f32_e32 v83, 1.0, v83
	v_fma_f32 v19, v83, v19, v51
	v_cvt_pk_bf16_f32 v16, v16, v17
	v_cvt_pk_bf16_f32 v17, v18, v19
	global_store_dwordx2 v228, v[16:17], s[10:11] offset:2048
	v_mul_f32_e32 v20, v20, v230
	v_mul_f32_e32 v20, v214, v20
	v_add_f32_e32 v84, 1.0, v84
	v_fma_f32 v20, v84, v20, v52
	v_mul_f32_e32 v21, v21, v230
	v_mul_f32_e32 v21, v215, v21
	v_add_f32_e32 v85, 1.0, v85
	v_fma_f32 v21, v85, v21, v53
	v_mul_f32_e32 v22, v22, v230
	v_mul_f32_e32 v22, v216, v22
	v_add_f32_e32 v86, 1.0, v86
	v_fma_f32 v22, v86, v22, v54
	v_mul_f32_e32 v23, v23, v230
	v_mul_f32_e32 v23, v217, v23
	v_add_f32_e32 v87, 1.0, v87
	v_fma_f32 v23, v87, v23, v55
	v_cvt_pk_bf16_f32 v20, v20, v21
	v_cvt_pk_bf16_f32 v21, v22, v23
	global_store_dwordx2 v228, v[20:21], s[10:11] offset:2560
	v_mul_f32_e32 v24, v24, v230
	v_mul_f32_e32 v24, v218, v24
	v_add_f32_e32 v88, 1.0, v88
	v_fma_f32 v24, v88, v24, v56
	v_mul_f32_e32 v25, v25, v230
	v_mul_f32_e32 v25, v219, v25
	v_add_f32_e32 v89, 1.0, v89
	v_fma_f32 v25, v89, v25, v57
	v_mul_f32_e32 v26, v26, v230
	v_mul_f32_e32 v26, v220, v26
	v_add_f32_e32 v90, 1.0, v90
	v_fma_f32 v26, v90, v26, v58
	v_mul_f32_e32 v27, v27, v230
	v_mul_f32_e32 v27, v221, v27
	v_add_f32_e32 v91, 1.0, v91
	v_fma_f32 v27, v91, v27, v59
	v_cvt_pk_bf16_f32 v24, v24, v25
	v_cvt_pk_bf16_f32 v25, v26, v27
	global_store_dwordx2 v228, v[24:25], s[10:11] offset:3072
	v_mul_f32_e32 v28, v28, v230
	v_mul_f32_e32 v28, v222, v28
	v_add_f32_e32 v92, 1.0, v92
	v_fma_f32 v28, v92, v28, v60
	v_mul_f32_e32 v29, v29, v230
	v_mul_f32_e32 v29, v223, v29
	v_add_f32_e32 v93, 1.0, v93
	v_fma_f32 v29, v93, v29, v61
	v_mul_f32_e32 v30, v30, v230
	v_mul_f32_e32 v30, v224, v30
	v_add_f32_e32 v94, 1.0, v94
	v_fma_f32 v30, v94, v30, v62
	v_mul_f32_e32 v31, v31, v230
	v_mul_f32_e32 v31, v225, v31
	v_add_f32_e32 v95, 1.0, v95
	v_fma_f32 v31, v95, v31, v63
	v_cvt_pk_bf16_f32 v28, v28, v29
	v_cvt_pk_bf16_f32 v29, v30, v31
	global_store_dwordx2 v228, v[28:29], s[10:11] offset:3584
.Lpost_next:
	s_add_u32 s16, s16, 0x800
	s_movk_i32 s9, 0x4000
	s_cmp_eq_u32 s40, 0
	s_cselect_b32 s9, 0x4400, s9
	s_cmp_lt_u32 s16, s9
	s_cbranch_scc1 .Lpost_row
.Lpost_done:
	s_mov_b64 s[20:21], exec
	s_branch .LBB0_1290
